# rwkv_post token loop batched 4 tokens per round trip; rms_rows loads issued together; attention V^T LDS swizzle + ds_read_b64
# baseline (speedup 1.0000x reference)
; __device__ __forceinline__ float sum8_dpp(float v) { v += dppf<0xB1>(v); v += dppf<0x4E>(v); v += dppf<0x141>(v); return v; }
; __device__ __forceinline__ void rwkv_post(const Ctx& c, const Params& p, int o) {
;     const bf16_t* RKV = (const bf16_t*)(c.ws + WS_RKV); const bf16_t* LO = (const bf16_t*)(c.ws + WS_LO); bf16_t* Y = (bf16_t*)(c.ws + WS_AB);
;     const float* lnw = p.in[c.zo + 23] + (size_t)o * 512; const float* lnb = p.in[c.zo + 24] + (size_t)o * 512; const float* BON = (const float*)(c.ws + WS_LA);
;     const int h = c.lane >> 3, c8 = h * 64 + 8 * (c.lane & 7);
;     float lw[8], lb[8];
; #pragma unroll
;     for (int i = 0; i < 8; ++i) { lw[i] = lnw[c8 + i]; lb[i] = lnb[c8 + i]; }
;     for (int m = c.gw; m < M_; m += c.ngw) { const bf16_t* lo = LO + (size_t)m * 2048;
;         float y[8], v[8], g[8]; unpack8(*(const u32x4*)(lo + 1536 + c8), y); unpack8(*(const u32x4*)(RKV + (size_t)m * RKV_LD + 1024 + c8), v); unpack8(*(const u32x4*)(lo + 1024 + c8), g);
;         const float bon = BON[(size_t)m * 8 + h];
;         float s1 = 0.f;
; #pragma unroll
;         for (int i = 0; i < 8; ++i) s1 += y[i];
;         const float mean = sum8_dpp(s1) * (1.f / 64.f); float s2 = 0.f;
; #pragma unroll
;         for (int i = 0; i < 8; ++i) { y[i] -= mean; s2 += y[i] * y[i]; }
;         const float rs = rsqrtf(sum8_dpp(s2) * (1.f / 64.f) + 64e-5f); float out[8];
.LBB0_488:
	s_and_b64 vcc, exec, s[48:49]
	s_cbranch_vccz .LBB0_493
	s_cmpk_gt_i32 s28, 0x7fff
	s_cbranch_scc1 .LBB0_492
	v_readlane_b32 s0, v255, 26
	v_readlane_b32 s1, v255, 27
	s_lshl_b64 s[2:3], s[0:1], 3
	v_readlane_b32 s0, v255, 15
	v_readlane_b32 s1, v255, 16
	s_add_u32 s2, s0, s2
	s_addc_u32 s3, s1, s3
	s_load_dwordx4 s[4:7], s[2:3], 0xb8
	v_readlane_b32 s2, v255, 39
	v_readlane_b32 s3, v255, 40
	s_lshl_b32 s42, s2, 9
	v_lshlrev_b32_e32 v1, 3, v164
	s_lshl_b64 s[2:3], s[42:43], 2
	s_waitcnt vmcnt(0) lgkmcnt(0)
	v_ashrrev_i32_e32 v20, 3, v164
	s_add_u32 s4, s4, s2
	v_and_b32_e32 v1, 56, v1
	s_addc_u32 s5, s5, s3
	v_lshl_or_b32 v18, v20, 6, v1
	s_add_u32 s2, s6, s2
	v_ashrrev_i32_e32 v19, 31, v18
	s_addc_u32 s3, s7, s3
	v_lshlrev_b64 v[2:3], 2, v[18:19]
	v_lshl_add_u64 v[6:7], s[4:5], 0, v[2:3]
	v_lshl_add_u64 v[14:15], s[2:3], 0, v[2:3]
	global_load_dwordx4 v[2:5], v[6:7], off offset:16
	s_nop 0
	global_load_dwordx4 v[6:9], v[6:7], off
	s_nop 0
	global_load_dwordx4 v[10:13], v[14:15], off offset:16
	s_nop 0
	global_load_dwordx4 v[14:17], v[14:15], off
	s_ashr_i32 s29, s28, 31
	s_lshl_b64 s[2:3], s[28:29], 11
	s_add_u32 s2, s74, s2
	v_lshlrev_b64 v[24:25], 1, v[18:19]
	s_addc_u32 s3, s75, s3
	s_ashr_i32 s31, s30, 31
	v_lshl_add_u64 v[18:19], s[2:3], 0, v[24:25]
	s_lshl_b64 s[2:3], s[30:31], 11
	s_lshl_b64 s[4:5], s[28:29], 5
	s_add_u32 s4, s22, s4
	v_ashrrev_i32_e32 v21, 31, v20
	s_addc_u32 s5, s23, s5
	v_lshl_add_u64 v[20:21], v[20:21], 2, s[4:5]
	s_mov_b64 s[4:5], 0x13100000
	v_lshl_add_u64 v[20:21], v[20:21], 0, s[4:5]
	s_lshl_b64 s[4:5], s[30:31], 5
	s_mul_i32 s6, s28, 0xc00
	s_mul_hi_i32 s7, s28, 0xc00
	s_add_u32 s6, s22, s6
	s_addc_u32 s7, s23, s7
	s_lshl_b64 s[8:9], s[28:29], 12
	s_add_u32 s8, s22, s8
	s_addc_u32 s9, s23, s9
	v_lshl_add_u64 v[22:23], s[6:7], 0, v[24:25]
	s_mov_b64 s[6:7], 0x8100800
	v_lshl_add_u64 v[24:25], s[8:9], 0, v[24:25]
	s_mov_b64 s[8:9], 0x14900c00
	s_movk_i32 s1, 0x2000
	v_lshl_add_u64 v[22:23], v[22:23], 0, s[6:7]
	s_mul_hi_i32 s7, s30, 0xc00
	s_mul_i32 s6, s30, 0xc00
	v_lshl_add_u64 v[24:25], v[24:25], 0, s[8:9]
	s_lshl_b64 s[8:9], s[30:31], 12
	s_mov_b32 s10, s28
	s_cmpk_lg_i32 s30, 0x800
	s_cbranch_scc1 .LBB0_491
.Lrp_batch:
	global_load_dwordx4 v[62:65], v[24:25], off
	global_load_dwordx4 v[66:69], v[22:23], off
	v_add_co_u32_e32 v70, vcc, 0xfffffc00, v24
	global_load_dword v60, v[20:21], off
	s_nop 0
	v_addc_co_u32_e32 v71, vcc, -1, v25, vcc
	global_load_dwordx4 v[70:73], v[70:71], off
	v_mov_b32_e32 v61, 0x3a27c5ac
	v_lshl_add_u64 v[20:21], v[20:21], 0, s[4:5]
	v_lshl_add_u64 v[22:23], v[22:23], 0, s[6:7]
	v_lshl_add_u64 v[24:25], v[24:25], 0, s[8:9]
	global_load_dwordx4 v[76:79], v[24:25], off
	global_load_dwordx4 v[80:83], v[22:23], off
	v_add_co_u32_e32 v84, vcc, 0xfffffc00, v24
	global_load_dword v74, v[20:21], off
	s_nop 0
	v_addc_co_u32_e32 v85, vcc, -1, v25, vcc
	global_load_dwordx4 v[84:87], v[84:85], off
	v_mov_b32_e32 v75, 0x3a27c5ac
	v_lshl_add_u64 v[20:21], v[20:21], 0, s[4:5]
	v_lshl_add_u64 v[22:23], v[22:23], 0, s[6:7]
	v_lshl_add_u64 v[24:25], v[24:25], 0, s[8:9]
	global_load_dwordx4 v[90:93], v[24:25], off
	global_load_dwordx4 v[94:97], v[22:23], off
	v_add_co_u32_e32 v98, vcc, 0xfffffc00, v24
	global_load_dword v88, v[20:21], off
	s_nop 0
	v_addc_co_u32_e32 v99, vcc, -1, v25, vcc
	global_load_dwordx4 v[98:101], v[98:99], off
	v_mov_b32_e32 v89, 0x3a27c5ac
	v_lshl_add_u64 v[20:21], v[20:21], 0, s[4:5]
	v_lshl_add_u64 v[22:23], v[22:23], 0, s[6:7]
	v_lshl_add_u64 v[24:25], v[24:25], 0, s[8:9]
	global_load_dwordx4 v[104:107], v[24:25], off
	global_load_dwordx4 v[108:111], v[22:23], off
	v_add_co_u32_e32 v112, vcc, 0xfffffc00, v24
	global_load_dword v102, v[20:21], off
	s_nop 0
	v_addc_co_u32_e32 v113, vcc, -1, v25, vcc
	global_load_dwordx4 v[112:115], v[112:113], off
	v_mov_b32_e32 v103, 0x3a27c5ac
	v_lshl_add_u64 v[20:21], v[20:21], 0, s[4:5]
	v_lshl_add_u64 v[22:23], v[22:23], 0, s[6:7]
	v_lshl_add_u64 v[24:25], v[24:25], 0, s[8:9]
	s_lshl_b32 s11, s30, 2
	s_add_i32 s10, s10, s11
	s_waitcnt vmcnt(12)
	v_lshlrev_b32_e32 v48, 16, v62
	v_and_b32_e32 v49, 0xffff0000, v62
	v_add_f32_e32 v1, 0, v48
	v_lshlrev_b32_e32 v40, 16, v65
	v_and_b32_e32 v41, 0xffff0000, v65
	v_lshlrev_b32_e32 v44, 16, v64
	v_and_b32_e32 v45, 0xffff0000, v64
	v_lshlrev_b32_e32 v64, 16, v68
	v_and_b32_e32 v65, 0xffff0000, v68
	v_lshlrev_b32_e32 v68, 16, v63
	v_add_f32_e32 v1, v1, v49
	v_lshlrev_b32_e32 v42, 16, v69
	v_and_b32_e32 v43, 0xffff0000, v69
	v_and_b32_e32 v69, 0xffff0000, v63
	v_add_f32_e32 v1, v1, v68
	v_add_f32_e32 v1, v1, v69
	v_add_f32_e32 v1, v1, v44
	v_add_f32_e32 v1, v1, v45
	v_add_f32_e32 v1, v1, v40
	v_add_f32_e32 v1, v1, v41
	v_lshlrev_b32_e32 v52, 16, v70
	v_and_b32_e32 v53, 0xffff0000, v70
	v_add_f32_dpp v1, v1, v1 quad_perm:[1,0,3,2] row_mask:0xf bank_mask:0xf bound_ctrl:1
	v_lshlrev_b32_e32 v46, 16, v67
	v_and_b32_e32 v47, 0xffff0000, v67
	v_add_f32_dpp v1, v1, v1 quad_perm:[2,3,0,1] row_mask:0xf bank_mask:0xf bound_ctrl:1
	v_lshlrev_b32_e32 v62, 16, v66
	v_and_b32_e32 v63, 0xffff0000, v66
	v_add_f32_dpp v1, v1, v1 row_half_mirror row_mask:0xf bank_mask:0xf bound_ctrl:1
	v_mul_f32_e32 v70, 0x3c800000, v1
	v_pk_add_f32 v[48:49], v[48:49], v[70:71] op_sel_hi:[1,0] neg_lo:[0,1] neg_hi:[0,1]
	v_lshlrev_b32_e32 v66, 16, v73
	v_and_b32_e32 v67, 0xffff0000, v73
	v_lshlrev_b32_e32 v50, 16, v72
	v_and_b32_e32 v51, 0xffff0000, v72
	v_lshlrev_b32_e32 v72, 16, v71
	v_and_b32_e32 v73, 0xffff0000, v71
	v_pk_add_f32 v[68:69], v[68:69], v[70:71] op_sel_hi:[1,0] neg_lo:[0,1] neg_hi:[0,1]
	v_pk_add_f32 v[44:45], v[44:45], v[70:71] op_sel_hi:[1,0] neg_lo:[0,1] neg_hi:[0,1]
; __device__ __forceinline__ u32x4 pack8(const float* f) { u32x4 o; o.x = pk2(f[0], f[1]); o.y = pk2(f[2], f[3]); o.z = pk2(f[4], f[5]); o.w = pk2(f[6], f[7]); return o; }
; __device__ __forceinline__ float sum8_dpp(float v) { v += dppf<0xB1>(v); v += dppf<0x4E>(v); v += dppf<0x141>(v); return v; }
; __device__ __forceinline__ void rwkv_post(const Ctx& c, const Params& p, int o) {
;     ...
;         float y[8], v[8], g[8]; unpack8(*(const u32x4*)(lo + 1536 + c8), y); unpack8(*(const u32x4*)(RKV + (size_t)m * RKV_LD + 1024 + c8), v); unpack8(*(const u32x4*)(lo + 1024 + c8), g);
;         const float bon = BON[(size_t)m * 8 + h];
;         float s1 = 0.f;
; #pragma unroll
;         for (int i = 0; i < 8; ++i) s1 += y[i];
;         const float mean = sum8_dpp(s1) * (1.f / 64.f); float s2 = 0.f;
; #pragma unroll
;         for (int i = 0; i < 8; ++i) { y[i] -= mean; s2 += y[i] * y[i]; }
;         const float rs = rsqrtf(sum8_dpp(s2) * (1.f / 64.f) + 64e-5f); float out[8];
; #pragma unroll
;         for (int i = 0; i < 8; ++i) out[i] = (y[i] * rs * lw[i] + lb[i] + bon * v[i]) * g[i];
;         *(u32x4*)(Y + (size_t)m * D_ + c8) = pack8(out); }
	v_pk_add_f32 v[70:71], v[40:41], v[70:71] op_sel_hi:[1,0] neg_lo:[0,1] neg_hi:[0,1]
	v_pk_mul_f32 v[40:41], v[48:49], v[48:49]
	v_pk_mul_f32 v[54:55], v[68:69], v[68:69]
	v_add_f32_e32 v1, v40, v41
	v_add_f32_e32 v1, v54, v1
	v_pk_mul_f32 v[56:57], v[44:45], v[44:45]
	v_add_f32_e32 v1, v55, v1
	v_add_f32_e32 v1, v56, v1
	v_pk_mul_f32 v[58:59], v[70:71], v[70:71]
	v_add_f32_e32 v1, v57, v1
	v_add_f32_e32 v1, v58, v1
	v_add_f32_e32 v1, v59, v1
	s_nop 1
	v_add_f32_dpp v1, v1, v1 quad_perm:[1,0,3,2] row_mask:0xf bank_mask:0xf bound_ctrl:1
	s_nop 1
	v_add_f32_dpp v1, v1, v1 quad_perm:[2,3,0,1] row_mask:0xf bank_mask:0xf bound_ctrl:1
	s_nop 1
	v_add_f32_dpp v1, v1, v1 row_half_mirror row_mask:0xf bank_mask:0xf bound_ctrl:1
	v_fmamk_f32 v1, v1, 0x3c800000, v61
	v_mul_f32_e32 v61, 0x4b800000, v1
	v_cmp_gt_f32_e32 vcc, s33, v1
	s_nop 1
	v_cndmask_b32_e32 v1, v1, v61, vcc
	v_rsq_f32_e32 v1, v1
	s_nop 0
	v_mul_f32_e32 v61, 0x45800000, v1
	v_cndmask_b32_e32 v40, v1, v61, vcc
	v_pk_mul_f32 v[48:49], v[48:49], v[40:41] op_sel_hi:[1,0]
	v_pk_mul_f32 v[68:69], v[68:69], v[40:41] op_sel_hi:[1,0]
	v_pk_mul_f32 v[44:45], v[44:45], v[40:41] op_sel_hi:[1,0]
	v_pk_mul_f32 v[70:71], v[70:71], v[40:41] op_sel_hi:[1,0]
	v_pk_fma_f32 v[40:41], v[6:7], v[48:49], v[14:15]
	v_pk_fma_f32 v[68:69], v[8:9], v[68:69], v[16:17]
	v_pk_fma_f32 v[44:45], v[2:3], v[44:45], v[10:11]
	v_pk_fma_f32 v[70:71], v[4:5], v[70:71], v[12:13]
	v_pk_fma_f32 v[62:63], v[60:61], v[62:63], v[40:41] op_sel_hi:[0,1,1]
	v_pk_fma_f32 v[68:69], v[60:61], v[46:47], v[68:69] op_sel_hi:[0,1,1]
	v_pk_fma_f32 v[64:65], v[60:61], v[64:65], v[44:45] op_sel_hi:[0,1,1]
	v_pk_fma_f32 v[60:61], v[60:61], v[42:43], v[70:71] op_sel_hi:[0,1,1]
	v_pk_mul_f32 v[62:63], v[62:63], v[52:53]
	v_pk_mul_f32 v[68:69], v[68:69], v[72:73]
	v_pk_mul_f32 v[64:65], v[64:65], v[50:51]
	v_pk_mul_f32 v[66:67], v[60:61], v[66:67]
	v_cvt_pk_bf16_f32 v60, v62, v63
	v_cvt_pk_bf16_f32 v61, v68, v69
	v_cvt_pk_bf16_f32 v62, v64, v65
	v_cvt_pk_bf16_f32 v63, v66, v67
	global_store_dwordx4 v[18:19], v[60:63], off
	v_lshl_add_u64 v[18:19], v[18:19], 0, s[2:3]
	s_waitcnt vmcnt(9)
	v_lshlrev_b32_e32 v48, 16, v76
	v_and_b32_e32 v49, 0xffff0000, v76
	v_add_f32_e32 v1, 0, v48
	v_lshlrev_b32_e32 v40, 16, v79
	v_and_b32_e32 v41, 0xffff0000, v79
	v_lshlrev_b32_e32 v44, 16, v78
	v_and_b32_e32 v45, 0xffff0000, v78
	v_lshlrev_b32_e32 v78, 16, v82
	v_and_b32_e32 v79, 0xffff0000, v82
	v_lshlrev_b32_e32 v82, 16, v77
	v_add_f32_e32 v1, v1, v49
	v_lshlrev_b32_e32 v42, 16, v83
	v_and_b32_e32 v43, 0xffff0000, v83
	v_and_b32_e32 v83, 0xffff0000, v77
	v_add_f32_e32 v1, v1, v82
	v_add_f32_e32 v1, v1, v83
	v_add_f32_e32 v1, v1, v44
	v_add_f32_e32 v1, v1, v45
	v_add_f32_e32 v1, v1, v40
	v_add_f32_e32 v1, v1, v41
	v_lshlrev_b32_e32 v52, 16, v84
	v_and_b32_e32 v53, 0xffff0000, v84
	v_add_f32_dpp v1, v1, v1 quad_perm:[1,0,3,2] row_mask:0xf bank_mask:0xf bound_ctrl:1
	v_lshlrev_b32_e32 v46, 16, v81
	v_and_b32_e32 v47, 0xffff0000, v81
	v_add_f32_dpp v1, v1, v1 quad_perm:[2,3,0,1] row_mask:0xf bank_mask:0xf bound_ctrl:1
	v_lshlrev_b32_e32 v76, 16, v80
	v_and_b32_e32 v77, 0xffff0000, v80
	v_add_f32_dpp v1, v1, v1 row_half_mirror row_mask:0xf bank_mask:0xf bound_ctrl:1
	v_mul_f32_e32 v84, 0x3c800000, v1
	v_pk_add_f32 v[48:49], v[48:49], v[84:85] op_sel_hi:[1,0] neg_lo:[0,1] neg_hi:[0,1]
	v_lshlrev_b32_e32 v80, 16, v87
	v_and_b32_e32 v81, 0xffff0000, v87
	v_lshlrev_b32_e32 v50, 16, v86
	v_and_b32_e32 v51, 0xffff0000, v86
	v_lshlrev_b32_e32 v86, 16, v85
	v_and_b32_e32 v87, 0xffff0000, v85
	v_pk_add_f32 v[82:83], v[82:83], v[84:85] op_sel_hi:[1,0] neg_lo:[0,1] neg_hi:[0,1]
	v_pk_add_f32 v[44:45], v[44:45], v[84:85] op_sel_hi:[1,0] neg_lo:[0,1] neg_hi:[0,1]
	v_pk_add_f32 v[84:85], v[40:41], v[84:85] op_sel_hi:[1,0] neg_lo:[0,1] neg_hi:[0,1]
	v_pk_mul_f32 v[40:41], v[48:49], v[48:49]
	v_pk_mul_f32 v[54:55], v[82:83], v[82:83]
	v_add_f32_e32 v1, v40, v41
	v_add_f32_e32 v1, v54, v1
	v_pk_mul_f32 v[56:57], v[44:45], v[44:45]
	v_add_f32_e32 v1, v55, v1
	v_add_f32_e32 v1, v56, v1
	v_pk_mul_f32 v[58:59], v[84:85], v[84:85]
	v_add_f32_e32 v1, v57, v1
	v_add_f32_e32 v1, v58, v1
	v_add_f32_e32 v1, v59, v1
	s_nop 1
	v_add_f32_dpp v1, v1, v1 quad_perm:[1,0,3,2] row_mask:0xf bank_mask:0xf bound_ctrl:1
	s_nop 1
	v_add_f32_dpp v1, v1, v1 quad_perm:[2,3,0,1] row_mask:0xf bank_mask:0xf bound_ctrl:1
	s_nop 1
	v_add_f32_dpp v1, v1, v1 row_half_mirror row_mask:0xf bank_mask:0xf bound_ctrl:1
	v_fmamk_f32 v1, v1, 0x3c800000, v75
	v_mul_f32_e32 v75, 0x4b800000, v1
	v_cmp_gt_f32_e32 vcc, s33, v1
	s_nop 1
	v_cndmask_b32_e32 v1, v1, v75, vcc
	v_rsq_f32_e32 v1, v1
	s_nop 0
	v_mul_f32_e32 v75, 0x45800000, v1
	v_cndmask_b32_e32 v40, v1, v75, vcc
	v_pk_mul_f32 v[48:49], v[48:49], v[40:41] op_sel_hi:[1,0]
	v_pk_mul_f32 v[82:83], v[82:83], v[40:41] op_sel_hi:[1,0]
	v_pk_mul_f32 v[44:45], v[44:45], v[40:41] op_sel_hi:[1,0]
	v_pk_mul_f32 v[84:85], v[84:85], v[40:41] op_sel_hi:[1,0]
	v_pk_fma_f32 v[40:41], v[6:7], v[48:49], v[14:15]
	v_pk_fma_f32 v[82:83], v[8:9], v[82:83], v[16:17]
	v_pk_fma_f32 v[44:45], v[2:3], v[44:45], v[10:11]
	v_pk_fma_f32 v[84:85], v[4:5], v[84:85], v[12:13]
	v_pk_fma_f32 v[76:77], v[74:75], v[76:77], v[40:41] op_sel_hi:[0,1,1]
	v_pk_fma_f32 v[82:83], v[74:75], v[46:47], v[82:83] op_sel_hi:[0,1,1]
	v_pk_fma_f32 v[78:79], v[74:75], v[78:79], v[44:45] op_sel_hi:[0,1,1]
	v_pk_fma_f32 v[74:75], v[74:75], v[42:43], v[84:85] op_sel_hi:[0,1,1]
	v_pk_mul_f32 v[76:77], v[76:77], v[52:53]
	v_pk_mul_f32 v[82:83], v[82:83], v[86:87]
	v_pk_mul_f32 v[78:79], v[78:79], v[50:51]
	v_pk_mul_f32 v[80:81], v[74:75], v[80:81]
	v_cvt_pk_bf16_f32 v74, v76, v77
	v_cvt_pk_bf16_f32 v75, v82, v83
	v_cvt_pk_bf16_f32 v76, v78, v79
	v_cvt_pk_bf16_f32 v77, v80, v81
	global_store_dwordx4 v[18:19], v[74:77], off
	v_lshl_add_u64 v[18:19], v[18:19], 0, s[2:3]
	s_waitcnt vmcnt(6)
; __device__ __forceinline__ u32x4 pack8(const float* f) { u32x4 o; o.x = pk2(f[0], f[1]); o.y = pk2(f[2], f[3]); o.z = pk2(f[4], f[5]); o.w = pk2(f[6], f[7]); return o; }
; __device__ __forceinline__ float sum8_dpp(float v) { v += dppf<0xB1>(v); v += dppf<0x4E>(v); v += dppf<0x141>(v); return v; }
; __device__ __forceinline__ void rwkv_post(const Ctx& c, const Params& p, int o) {
;     ...
;         float y[8], v[8], g[8]; unpack8(*(const u32x4*)(lo + 1536 + c8), y); unpack8(*(const u32x4*)(RKV + (size_t)m * RKV_LD + 1024 + c8), v); unpack8(*(const u32x4*)(lo + 1024 + c8), g);
;         const float bon = BON[(size_t)m * 8 + h];
;         float s1 = 0.f;
; #pragma unroll
;         for (int i = 0; i < 8; ++i) s1 += y[i];
;         const float mean = sum8_dpp(s1) * (1.f / 64.f); float s2 = 0.f;
; #pragma unroll
;         for (int i = 0; i < 8; ++i) { y[i] -= mean; s2 += y[i] * y[i]; }
;         const float rs = rsqrtf(sum8_dpp(s2) * (1.f / 64.f) + 64e-5f); float out[8];
; #pragma unroll
;         for (int i = 0; i < 8; ++i) out[i] = (y[i] * rs * lw[i] + lb[i] + bon * v[i]) * g[i];
;         *(u32x4*)(Y + (size_t)m * D_ + c8) = pack8(out); }
	v_lshlrev_b32_e32 v48, 16, v90
	v_and_b32_e32 v49, 0xffff0000, v90
	v_add_f32_e32 v1, 0, v48
	v_lshlrev_b32_e32 v40, 16, v93
	v_and_b32_e32 v41, 0xffff0000, v93
	v_lshlrev_b32_e32 v44, 16, v92
	v_and_b32_e32 v45, 0xffff0000, v92
	v_lshlrev_b32_e32 v92, 16, v96
	v_and_b32_e32 v93, 0xffff0000, v96
	v_lshlrev_b32_e32 v96, 16, v91
	v_add_f32_e32 v1, v1, v49
	v_lshlrev_b32_e32 v42, 16, v97
	v_and_b32_e32 v43, 0xffff0000, v97
	v_and_b32_e32 v97, 0xffff0000, v91
	v_add_f32_e32 v1, v1, v96
	v_add_f32_e32 v1, v1, v97
	v_add_f32_e32 v1, v1, v44
	v_add_f32_e32 v1, v1, v45
	v_add_f32_e32 v1, v1, v40
	v_add_f32_e32 v1, v1, v41
	v_lshlrev_b32_e32 v52, 16, v98
	v_and_b32_e32 v53, 0xffff0000, v98
	v_add_f32_dpp v1, v1, v1 quad_perm:[1,0,3,2] row_mask:0xf bank_mask:0xf bound_ctrl:1
	v_lshlrev_b32_e32 v46, 16, v95
	v_and_b32_e32 v47, 0xffff0000, v95
	v_add_f32_dpp v1, v1, v1 quad_perm:[2,3,0,1] row_mask:0xf bank_mask:0xf bound_ctrl:1
	v_lshlrev_b32_e32 v90, 16, v94
	v_and_b32_e32 v91, 0xffff0000, v94
	v_add_f32_dpp v1, v1, v1 row_half_mirror row_mask:0xf bank_mask:0xf bound_ctrl:1
	v_mul_f32_e32 v98, 0x3c800000, v1
	v_pk_add_f32 v[48:49], v[48:49], v[98:99] op_sel_hi:[1,0] neg_lo:[0,1] neg_hi:[0,1]
	v_lshlrev_b32_e32 v94, 16, v101
	v_and_b32_e32 v95, 0xffff0000, v101
	v_lshlrev_b32_e32 v50, 16, v100
	v_and_b32_e32 v51, 0xffff0000, v100
	v_lshlrev_b32_e32 v100, 16, v99
	v_and_b32_e32 v101, 0xffff0000, v99
	v_pk_add_f32 v[96:97], v[96:97], v[98:99] op_sel_hi:[1,0] neg_lo:[0,1] neg_hi:[0,1]
	v_pk_add_f32 v[44:45], v[44:45], v[98:99] op_sel_hi:[1,0] neg_lo:[0,1] neg_hi:[0,1]
	v_pk_add_f32 v[98:99], v[40:41], v[98:99] op_sel_hi:[1,0] neg_lo:[0,1] neg_hi:[0,1]
	v_pk_mul_f32 v[40:41], v[48:49], v[48:49]
	v_pk_mul_f32 v[54:55], v[96:97], v[96:97]
	v_add_f32_e32 v1, v40, v41
	v_add_f32_e32 v1, v54, v1
	v_pk_mul_f32 v[56:57], v[44:45], v[44:45]
	v_add_f32_e32 v1, v55, v1
	v_add_f32_e32 v1, v56, v1
	v_pk_mul_f32 v[58:59], v[98:99], v[98:99]
	v_add_f32_e32 v1, v57, v1
	v_add_f32_e32 v1, v58, v1
	v_add_f32_e32 v1, v59, v1
	s_nop 1
	v_add_f32_dpp v1, v1, v1 quad_perm:[1,0,3,2] row_mask:0xf bank_mask:0xf bound_ctrl:1
	s_nop 1
	v_add_f32_dpp v1, v1, v1 quad_perm:[2,3,0,1] row_mask:0xf bank_mask:0xf bound_ctrl:1
	s_nop 1
	v_add_f32_dpp v1, v1, v1 row_half_mirror row_mask:0xf bank_mask:0xf bound_ctrl:1
	v_fmamk_f32 v1, v1, 0x3c800000, v89
	v_mul_f32_e32 v89, 0x4b800000, v1
	v_cmp_gt_f32_e32 vcc, s33, v1
	s_nop 1
	v_cndmask_b32_e32 v1, v1, v89, vcc
	v_rsq_f32_e32 v1, v1
	s_nop 0
	v_mul_f32_e32 v89, 0x45800000, v1
	v_cndmask_b32_e32 v40, v1, v89, vcc
	v_pk_mul_f32 v[48:49], v[48:49], v[40:41] op_sel_hi:[1,0]
	v_pk_mul_f32 v[96:97], v[96:97], v[40:41] op_sel_hi:[1,0]
	v_pk_mul_f32 v[44:45], v[44:45], v[40:41] op_sel_hi:[1,0]
	v_pk_mul_f32 v[98:99], v[98:99], v[40:41] op_sel_hi:[1,0]
	v_pk_fma_f32 v[40:41], v[6:7], v[48:49], v[14:15]
	v_pk_fma_f32 v[96:97], v[8:9], v[96:97], v[16:17]
	v_pk_fma_f32 v[44:45], v[2:3], v[44:45], v[10:11]
	v_pk_fma_f32 v[98:99], v[4:5], v[98:99], v[12:13]
	v_pk_fma_f32 v[90:91], v[88:89], v[90:91], v[40:41] op_sel_hi:[0,1,1]
	v_pk_fma_f32 v[96:97], v[88:89], v[46:47], v[96:97] op_sel_hi:[0,1,1]
	v_pk_fma_f32 v[92:93], v[88:89], v[92:93], v[44:45] op_sel_hi:[0,1,1]
	v_pk_fma_f32 v[88:89], v[88:89], v[42:43], v[98:99] op_sel_hi:[0,1,1]
	v_pk_mul_f32 v[90:91], v[90:91], v[52:53]
	v_pk_mul_f32 v[96:97], v[96:97], v[100:101]
	v_pk_mul_f32 v[92:93], v[92:93], v[50:51]
	v_pk_mul_f32 v[94:95], v[88:89], v[94:95]
	v_cvt_pk_bf16_f32 v88, v90, v91
	v_cvt_pk_bf16_f32 v89, v96, v97
	v_cvt_pk_bf16_f32 v90, v92, v93
	v_cvt_pk_bf16_f32 v91, v94, v95
	global_store_dwordx4 v[18:19], v[88:91], off
	v_lshl_add_u64 v[18:19], v[18:19], 0, s[2:3]
	s_waitcnt vmcnt(3)
; __device__ __forceinline__ u32x4 pack8(const float* f) { u32x4 o; o.x = pk2(f[0], f[1]); o.y = pk2(f[2], f[3]); o.z = pk2(f[4], f[5]); o.w = pk2(f[6], f[7]); return o; }
; __device__ __forceinline__ float sum8_dpp(float v) { v += dppf<0xB1>(v); v += dppf<0x4E>(v); v += dppf<0x141>(v); return v; }
; __device__ __forceinline__ void rwkv_post(const Ctx& c, const Params& p, int o) {
;     ...
;         float y[8], v[8], g[8]; unpack8(*(const u32x4*)(lo + 1536 + c8), y); unpack8(*(const u32x4*)(RKV + (size_t)m * RKV_LD + 1024 + c8), v); unpack8(*(const u32x4*)(lo + 1024 + c8), g);
;         const float bon = BON[(size_t)m * 8 + h];
;         float s1 = 0.f;
; #pragma unroll
;         for (int i = 0; i < 8; ++i) s1 += y[i];
;         const float mean = sum8_dpp(s1) * (1.f / 64.f); float s2 = 0.f;
; #pragma unroll
;         for (int i = 0; i < 8; ++i) { y[i] -= mean; s2 += y[i] * y[i]; }
;         const float rs = rsqrtf(sum8_dpp(s2) * (1.f / 64.f) + 64e-5f); float out[8];
; #pragma unroll
;         for (int i = 0; i < 8; ++i) out[i] = (y[i] * rs * lw[i] + lb[i] + bon * v[i]) * g[i];
;         *(u32x4*)(Y + (size_t)m * D_ + c8) = pack8(out); }
	v_lshlrev_b32_e32 v48, 16, v104
	v_and_b32_e32 v49, 0xffff0000, v104
	v_add_f32_e32 v1, 0, v48
	v_lshlrev_b32_e32 v40, 16, v107
	v_and_b32_e32 v41, 0xffff0000, v107
	v_lshlrev_b32_e32 v44, 16, v106
	v_and_b32_e32 v45, 0xffff0000, v106
	v_lshlrev_b32_e32 v106, 16, v110
	v_and_b32_e32 v107, 0xffff0000, v110
	v_lshlrev_b32_e32 v110, 16, v105
	v_add_f32_e32 v1, v1, v49
	v_lshlrev_b32_e32 v42, 16, v111
	v_and_b32_e32 v43, 0xffff0000, v111
	v_and_b32_e32 v111, 0xffff0000, v105
	v_add_f32_e32 v1, v1, v110
	v_add_f32_e32 v1, v1, v111
	v_add_f32_e32 v1, v1, v44
	v_add_f32_e32 v1, v1, v45
	v_add_f32_e32 v1, v1, v40
	v_add_f32_e32 v1, v1, v41
	v_lshlrev_b32_e32 v52, 16, v112
	v_and_b32_e32 v53, 0xffff0000, v112
	v_add_f32_dpp v1, v1, v1 quad_perm:[1,0,3,2] row_mask:0xf bank_mask:0xf bound_ctrl:1
	v_lshlrev_b32_e32 v46, 16, v109
	v_and_b32_e32 v47, 0xffff0000, v109
	v_add_f32_dpp v1, v1, v1 quad_perm:[2,3,0,1] row_mask:0xf bank_mask:0xf bound_ctrl:1
	v_lshlrev_b32_e32 v104, 16, v108
	v_and_b32_e32 v105, 0xffff0000, v108
	v_add_f32_dpp v1, v1, v1 row_half_mirror row_mask:0xf bank_mask:0xf bound_ctrl:1
	v_mul_f32_e32 v112, 0x3c800000, v1
	v_pk_add_f32 v[48:49], v[48:49], v[112:113] op_sel_hi:[1,0] neg_lo:[0,1] neg_hi:[0,1]
	v_lshlrev_b32_e32 v108, 16, v115
	v_and_b32_e32 v109, 0xffff0000, v115
	v_lshlrev_b32_e32 v50, 16, v114
	v_and_b32_e32 v51, 0xffff0000, v114
	v_lshlrev_b32_e32 v114, 16, v113
	v_and_b32_e32 v115, 0xffff0000, v113
	v_pk_add_f32 v[110:111], v[110:111], v[112:113] op_sel_hi:[1,0] neg_lo:[0,1] neg_hi:[0,1]
	v_pk_add_f32 v[44:45], v[44:45], v[112:113] op_sel_hi:[1,0] neg_lo:[0,1] neg_hi:[0,1]
	v_pk_add_f32 v[112:113], v[40:41], v[112:113] op_sel_hi:[1,0] neg_lo:[0,1] neg_hi:[0,1]
	v_pk_mul_f32 v[40:41], v[48:49], v[48:49]
	v_pk_mul_f32 v[54:55], v[110:111], v[110:111]
	v_add_f32_e32 v1, v40, v41
	v_add_f32_e32 v1, v54, v1
	v_pk_mul_f32 v[56:57], v[44:45], v[44:45]
	v_add_f32_e32 v1, v55, v1
	v_add_f32_e32 v1, v56, v1
	v_pk_mul_f32 v[58:59], v[112:113], v[112:113]
	v_add_f32_e32 v1, v57, v1
	v_add_f32_e32 v1, v58, v1
	v_add_f32_e32 v1, v59, v1
	s_nop 1
	v_add_f32_dpp v1, v1, v1 quad_perm:[1,0,3,2] row_mask:0xf bank_mask:0xf bound_ctrl:1
	s_nop 1
	v_add_f32_dpp v1, v1, v1 quad_perm:[2,3,0,1] row_mask:0xf bank_mask:0xf bound_ctrl:1
	s_nop 1
	v_add_f32_dpp v1, v1, v1 row_half_mirror row_mask:0xf bank_mask:0xf bound_ctrl:1
	v_fmamk_f32 v1, v1, 0x3c800000, v103
	v_mul_f32_e32 v103, 0x4b800000, v1
	v_cmp_gt_f32_e32 vcc, s33, v1
	s_nop 1
	v_cndmask_b32_e32 v1, v1, v103, vcc
	v_rsq_f32_e32 v1, v1
	s_nop 0
	v_mul_f32_e32 v103, 0x45800000, v1
	v_cndmask_b32_e32 v40, v1, v103, vcc
	v_pk_mul_f32 v[48:49], v[48:49], v[40:41] op_sel_hi:[1,0]
	v_pk_mul_f32 v[110:111], v[110:111], v[40:41] op_sel_hi:[1,0]
	v_pk_mul_f32 v[44:45], v[44:45], v[40:41] op_sel_hi:[1,0]
	v_pk_mul_f32 v[112:113], v[112:113], v[40:41] op_sel_hi:[1,0]
	v_pk_fma_f32 v[40:41], v[6:7], v[48:49], v[14:15]
	v_pk_fma_f32 v[110:111], v[8:9], v[110:111], v[16:17]
	v_pk_fma_f32 v[44:45], v[2:3], v[44:45], v[10:11]
	v_pk_fma_f32 v[112:113], v[4:5], v[112:113], v[12:13]
	v_pk_fma_f32 v[104:105], v[102:103], v[104:105], v[40:41] op_sel_hi:[0,1,1]
	v_pk_fma_f32 v[110:111], v[102:103], v[46:47], v[110:111] op_sel_hi:[0,1,1]
	v_pk_fma_f32 v[106:107], v[102:103], v[106:107], v[44:45] op_sel_hi:[0,1,1]
	v_pk_fma_f32 v[102:103], v[102:103], v[42:43], v[112:113] op_sel_hi:[0,1,1]
	v_pk_mul_f32 v[104:105], v[104:105], v[52:53]
	v_pk_mul_f32 v[110:111], v[110:111], v[114:115]
	v_pk_mul_f32 v[106:107], v[106:107], v[50:51]
	v_pk_mul_f32 v[108:109], v[102:103], v[108:109]
	v_cvt_pk_bf16_f32 v102, v104, v105
	v_cvt_pk_bf16_f32 v103, v110, v111
	v_cvt_pk_bf16_f32 v104, v106, v107
	v_cvt_pk_bf16_f32 v105, v108, v109
	global_store_dwordx4 v[18:19], v[102:105], off
	v_lshl_add_u64 v[18:19], v[18:19], 0, s[2:3]
	s_cmpk_gt_i32 s10, 0x7fff
	s_cbranch_scc0 .Lrp_batch
	s_branch .LBB0_492
